# merge odd-epilogue rewrite: second-half gate/merged loads issued right behind each first-half store (reusing the freed registers), counted vmcnt waits
# speedup vs baseline: 1.0180x; 1.0180x over previous
; DI unsigned cvtpk(float lo, float hi) { typedef float f2 __attribute__((ext_vector_type(2))); typedef __bf16 b2 __attribute__((ext_vector_type(2))); f2 v = {lo, hi}; b2 b = __builtin_convertvector(v, b2); return __builtin_bit_cast(unsigned, b); }
; DI float bflo(unsigned w) { return __uint_as_float(w << 16); }
; DI float bfhi(unsigned w) { return __uint_as_float(w & 0xffff0000u); }
;     DI void operator()(f32x4 (&acc)[2][2][4][2], const pg8::GUnit& u, int wr, int wc, int fr, int fq) const {
;     ...
;             for (int ai = 0; ai < 2; ++ai) {
;                 u32x4 gq[4][2], mq[4][2];
; #pragma unroll
;                 for (int m = 0; m < 4; ++m) { const bf16_t* rp = act + (size_t)(row0 + ai * 128 + m * 16) * PITCH + col0;
; #pragma unroll
;                     for (int bj = 0; bj < 2; ++bj) { gq[m][bj] = *(const u32x4*)(rp + C_GS + bj * 128); if (z > 1) mq[m][bj] = *(const u32x4*)(rp + C_MERGED + bj * 128); } }
; #pragma unroll
;                 for (int m = 0; m < 4; ++m) { bf16_t* mp = act + (size_t)(row0 + ai * 128 + m * 16) * PITCH + C_MERGED + col0;
; #pragma unroll
;                     for (int bj = 0; bj < 2; ++bj) {
;                         const u32x4 g = gq[m][bj];
;                         const f32x4 a0 = acc[ai][bj][m][0], a1 = acc[ai][bj][m][1];
;                         float r0 = bflo(g.x) * a0[0], r1 = bfhi(g.x) * a0[1], r2 = bflo(g.y) * a0[2], r3 = bfhi(g.y) * a0[3];
;                         float r4 = bflo(g.z) * a1[0], r5 = bfhi(g.z) * a1[1], r6 = bflo(g.w) * a1[2], r7 = bfhi(g.w) * a1[3];
;                         if (z > 1) { const u32x4 pm_ = mq[m][bj];
;                             r0 += bflo(pm_.x); r1 += bfhi(pm_.x); r2 += bflo(pm_.y); r3 += bfhi(pm_.y); r4 += bflo(pm_.z); r5 += bfhi(pm_.z); r6 += bflo(pm_.w); r7 += bfhi(pm_.w); }
;                         u32x4 w; w.x = cvtpk(r0, r1); w.y = cvtpk(r2, r3); w.z = cvtpk(r4, r5); w.w = cvtpk(r6, r7);
;                         *(u32x4*)(mp + bj * 128) = w;
;                     } }
.LBB0_665:
	v_lshl_add_u32 v245, s57, 8, v240
	v_lshl_or_b32 v216, s56, 8, v243
	s_bitcmp0_b32 s58, 0
	s_mov_b64 s[22:23], -1
	s_cbranch_scc1 .LBB0_731
	v_ashrrev_i32_e32 v217, 31, v216
	v_lshl_add_u64 v[218:219], v[216:217], 1, s[6:7]
	v_mad_i64_i32 v[252:253], vcc, v245, s31, v[218:219]
	s_lshl_b32 s98, s31, 4
	s_mov_b32 s99, 0
	s_movk_i32 s100, 0x1000
	s_mov_b32 s101, 0
	s_cmp_gt_i32 s58, 1
	s_cselect_b64 s[44:45], 0, -1
	v_mov_b32_e32 v254, v252
	v_mov_b32_e32 v255, v253
	s_and_b64 vcc, exec, s[44:45]
	s_cbranch_vccnz .Lmo_ld1_nm
	v_lshl_add_u64 v[186:187], v[254:255], 0, s[100:101]
	global_load_dwordx4 v[190:193], v[186:187], off offset:1024
	global_load_dwordx4 v[186:189], v[186:187], off offset:1280
	global_load_dwordx4 v[158:161], v[254:255], off offset:1024
	global_load_dwordx4 v[154:157], v[254:255], off offset:1280
	v_lshl_add_u64 v[254:255], v[254:255], 0, s[98:99]
	v_lshl_add_u64 v[178:179], v[254:255], 0, s[100:101]
	global_load_dwordx4 v[182:185], v[178:179], off offset:1024
	global_load_dwordx4 v[178:181], v[178:179], off offset:1280
	global_load_dwordx4 v[150:153], v[254:255], off offset:1024
	global_load_dwordx4 v[146:149], v[254:255], off offset:1280
	v_lshl_add_u64 v[254:255], v[254:255], 0, s[98:99]
	v_lshl_add_u64 v[170:171], v[254:255], 0, s[100:101]
	global_load_dwordx4 v[174:177], v[170:171], off offset:1024
	global_load_dwordx4 v[170:173], v[170:171], off offset:1280
	global_load_dwordx4 v[142:145], v[254:255], off offset:1024
	global_load_dwordx4 v[138:141], v[254:255], off offset:1280
	v_lshl_add_u64 v[254:255], v[254:255], 0, s[98:99]
	v_lshl_add_u64 v[162:163], v[254:255], 0, s[100:101]
	global_load_dwordx4 v[166:169], v[162:163], off offset:1024
	global_load_dwordx4 v[162:165], v[162:163], off offset:1280
	global_load_dwordx4 v[134:137], v[254:255], off offset:1024
	global_load_dwordx4 v[130:133], v[254:255], off offset:1280
	s_branch .Lmo_ld1_done
.Lmo_ld1_nm:
	v_lshl_add_u64 v[186:187], v[254:255], 0, s[100:101]
	global_load_dwordx4 v[190:193], v[186:187], off offset:1024
	global_load_dwordx4 v[186:189], v[186:187], off offset:1280
	v_lshl_add_u64 v[254:255], v[254:255], 0, s[98:99]
	v_lshl_add_u64 v[178:179], v[254:255], 0, s[100:101]
	global_load_dwordx4 v[182:185], v[178:179], off offset:1024
	global_load_dwordx4 v[178:181], v[178:179], off offset:1280
	v_lshl_add_u64 v[254:255], v[254:255], 0, s[98:99]
	v_lshl_add_u64 v[170:171], v[254:255], 0, s[100:101]
	global_load_dwordx4 v[174:177], v[170:171], off offset:1024
	global_load_dwordx4 v[170:173], v[170:171], off offset:1280
	v_lshl_add_u64 v[254:255], v[254:255], 0, s[98:99]
	v_lshl_add_u64 v[162:163], v[254:255], 0, s[100:101]
	global_load_dwordx4 v[166:169], v[162:163], off offset:1024
	global_load_dwordx4 v[162:165], v[162:163], off offset:1280
.Lmo_ld1_done:
	s_lshl_b32 s100, s31, 7
	s_add_u32 s22, s100, 0x1000
	s_mov_b32 s23, 0
	s_waitcnt vmcnt(0)
	s_and_b64 vcc, exec, s[44:45]
	s_cbranch_vccnz .Lmo_h1nm_0
	v_lshlrev_b32_e32 v218, 16, v190
	v_and_b32_e32 v219, 0xffff0000, v190
	v_lshlrev_b32_e32 v220, 16, v191
	v_and_b32_e32 v221, 0xffff0000, v191
	v_lshlrev_b32_e32 v222, 16, v192
	v_and_b32_e32 v223, 0xffff0000, v192
	v_lshlrev_b32_e32 v224, 16, v193
	v_and_b32_e32 v225, 0xffff0000, v193
	v_pk_mul_f32 v[218:219], v[126:127], v[218:219]
	v_pk_mul_f32 v[220:221], v[128:129], v[220:221]
	v_pk_mul_f32 v[222:223], v[122:123], v[222:223]
	v_pk_mul_f32 v[224:225], v[124:125], v[224:225]
	v_lshlrev_b32_e32 v190, 16, v158
	v_and_b32_e32 v191, 0xffff0000, v158
	v_pk_add_f32 v[218:219], v[218:219], v[190:191]
	v_lshlrev_b32_e32 v192, 16, v159
	v_and_b32_e32 v193, 0xffff0000, v159
	v_pk_add_f32 v[220:221], v[220:221], v[192:193]
	v_lshlrev_b32_e32 v190, 16, v160
	v_and_b32_e32 v191, 0xffff0000, v160
	v_pk_add_f32 v[222:223], v[222:223], v[190:191]
	v_lshlrev_b32_e32 v192, 16, v161
	v_and_b32_e32 v193, 0xffff0000, v161
	v_pk_add_f32 v[224:225], v[224:225], v[192:193]
	v_cvt_pk_bf16_f32 v218, v218, v219
	v_cvt_pk_bf16_f32 v219, v220, v221
	v_cvt_pk_bf16_f32 v220, v222, v223
	v_cvt_pk_bf16_f32 v221, v224, v225
	global_store_dwordx4 v[252:253], v[218:221], off offset:1024
	v_lshl_add_u64 v[190:191], v[252:253], 0, s[22:23]
	v_lshl_add_u64 v[158:159], v[252:253], 0, s[100:101]
	global_load_dwordx4 v[190:193], v[190:191], off offset:1024
	global_load_dwordx4 v[158:161], v[158:159], off offset:1024
	s_branch .Lmo_h1e_0
.Lmo_h1nm_0:
	v_lshlrev_b32_e32 v218, 16, v190
	v_and_b32_e32 v219, 0xffff0000, v190
	v_lshlrev_b32_e32 v220, 16, v191
	v_and_b32_e32 v221, 0xffff0000, v191
	v_lshlrev_b32_e32 v222, 16, v192
	v_and_b32_e32 v223, 0xffff0000, v192
	v_lshlrev_b32_e32 v224, 16, v193
	v_and_b32_e32 v225, 0xffff0000, v193
	v_pk_mul_f32 v[218:219], v[126:127], v[218:219]
	v_pk_mul_f32 v[220:221], v[128:129], v[220:221]
	v_pk_mul_f32 v[222:223], v[122:123], v[222:223]
	v_pk_mul_f32 v[224:225], v[124:125], v[224:225]
	v_cvt_pk_bf16_f32 v218, v218, v219
	v_cvt_pk_bf16_f32 v219, v220, v221
	v_cvt_pk_bf16_f32 v220, v222, v223
	v_cvt_pk_bf16_f32 v221, v224, v225
	global_store_dwordx4 v[252:253], v[218:221], off offset:1024
	v_lshl_add_u64 v[190:191], v[252:253], 0, s[22:23]
	s_nop 0
	global_load_dwordx4 v[190:193], v[190:191], off offset:1024
; DI unsigned cvtpk(float lo, float hi) { typedef float f2 __attribute__((ext_vector_type(2))); typedef __bf16 b2 __attribute__((ext_vector_type(2))); f2 v = {lo, hi}; b2 b = __builtin_convertvector(v, b2); return __builtin_bit_cast(unsigned, b); }
; DI float bflo(unsigned w) { return __uint_as_float(w << 16); }
; DI float bfhi(unsigned w) { return __uint_as_float(w & 0xffff0000u); }
;     DI void operator()(f32x4 (&acc)[2][2][4][2], const pg8::GUnit& u, int wr, int wc, int fr, int fq) const {
;     ...
;                 for (int m = 0; m < 4; ++m) { bf16_t* mp = act + (size_t)(row0 + ai * 128 + m * 16) * PITCH + C_MERGED + col0;
; #pragma unroll
;                     for (int bj = 0; bj < 2; ++bj) {
;                         const u32x4 g = gq[m][bj];
;                         const f32x4 a0 = acc[ai][bj][m][0], a1 = acc[ai][bj][m][1];
;                         float r0 = bflo(g.x) * a0[0], r1 = bfhi(g.x) * a0[1], r2 = bflo(g.y) * a0[2], r3 = bfhi(g.y) * a0[3];
;                         float r4 = bflo(g.z) * a1[0], r5 = bfhi(g.z) * a1[1], r6 = bflo(g.w) * a1[2], r7 = bfhi(g.w) * a1[3];
;                         if (z > 1) { const u32x4 pm_ = mq[m][bj];
;                             r0 += bflo(pm_.x); r1 += bfhi(pm_.x); r2 += bflo(pm_.y); r3 += bfhi(pm_.y); r4 += bflo(pm_.z); r5 += bfhi(pm_.z); r6 += bflo(pm_.w); r7 += bfhi(pm_.w); }
;                         u32x4 w; w.x = cvtpk(r0, r1); w.y = cvtpk(r2, r3); w.z = cvtpk(r4, r5); w.w = cvtpk(r6, r7);
;                         *(u32x4*)(mp + bj * 128) = w;
;                     } }
.Lmo_h1e_0:
	s_and_b64 vcc, exec, s[44:45]
	s_cbranch_vccnz .Lmo_h1nm_1
	v_lshlrev_b32_e32 v218, 16, v186
	v_and_b32_e32 v219, 0xffff0000, v186
	v_lshlrev_b32_e32 v220, 16, v187
	v_and_b32_e32 v221, 0xffff0000, v187
	v_lshlrev_b32_e32 v222, 16, v188
	v_and_b32_e32 v223, 0xffff0000, v188
	v_lshlrev_b32_e32 v224, 16, v189
	v_and_b32_e32 v225, 0xffff0000, v189
	v_pk_mul_f32 v[218:219], v[118:119], v[218:219]
	v_pk_mul_f32 v[220:221], v[120:121], v[220:221]
	v_pk_mul_f32 v[222:223], v[114:115], v[222:223]
	v_pk_mul_f32 v[224:225], v[116:117], v[224:225]
	v_lshlrev_b32_e32 v186, 16, v154
	v_and_b32_e32 v187, 0xffff0000, v154
	v_pk_add_f32 v[218:219], v[218:219], v[186:187]
	v_lshlrev_b32_e32 v188, 16, v155
	v_and_b32_e32 v189, 0xffff0000, v155
	v_pk_add_f32 v[220:221], v[220:221], v[188:189]
	v_lshlrev_b32_e32 v186, 16, v156
	v_and_b32_e32 v187, 0xffff0000, v156
	v_pk_add_f32 v[222:223], v[222:223], v[186:187]
	v_lshlrev_b32_e32 v188, 16, v157
	v_and_b32_e32 v189, 0xffff0000, v157
	v_pk_add_f32 v[224:225], v[224:225], v[188:189]
	v_cvt_pk_bf16_f32 v218, v218, v219
	v_cvt_pk_bf16_f32 v219, v220, v221
	v_cvt_pk_bf16_f32 v220, v222, v223
	v_cvt_pk_bf16_f32 v221, v224, v225
	global_store_dwordx4 v[252:253], v[218:221], off offset:1280
	v_lshl_add_u64 v[186:187], v[252:253], 0, s[22:23]
	v_lshl_add_u64 v[154:155], v[252:253], 0, s[100:101]
	global_load_dwordx4 v[186:189], v[186:187], off offset:1280
	global_load_dwordx4 v[154:157], v[154:155], off offset:1280
	s_branch .Lmo_h1e_1
.Lmo_h1nm_1:
	v_lshlrev_b32_e32 v218, 16, v186
	v_and_b32_e32 v219, 0xffff0000, v186
	v_lshlrev_b32_e32 v220, 16, v187
	v_and_b32_e32 v221, 0xffff0000, v187
	v_lshlrev_b32_e32 v222, 16, v188
	v_and_b32_e32 v223, 0xffff0000, v188
	v_lshlrev_b32_e32 v224, 16, v189
	v_and_b32_e32 v225, 0xffff0000, v189
	v_pk_mul_f32 v[218:219], v[118:119], v[218:219]
	v_pk_mul_f32 v[220:221], v[120:121], v[220:221]
	v_pk_mul_f32 v[222:223], v[114:115], v[222:223]
	v_pk_mul_f32 v[224:225], v[116:117], v[224:225]
	v_cvt_pk_bf16_f32 v218, v218, v219
	v_cvt_pk_bf16_f32 v219, v220, v221
	v_cvt_pk_bf16_f32 v220, v222, v223
	v_cvt_pk_bf16_f32 v221, v224, v225
	global_store_dwordx4 v[252:253], v[218:221], off offset:1280
	v_lshl_add_u64 v[186:187], v[252:253], 0, s[22:23]
	s_nop 0
	global_load_dwordx4 v[186:189], v[186:187], off offset:1280
.Lmo_h1e_1:
	v_lshl_add_u64 v[252:253], v[252:253], 0, s[98:99]
	s_and_b64 vcc, exec, s[44:45]
	s_cbranch_vccnz .Lmo_h1nm_2
	v_lshlrev_b32_e32 v218, 16, v182
	v_and_b32_e32 v219, 0xffff0000, v182
	v_lshlrev_b32_e32 v220, 16, v183
	v_and_b32_e32 v221, 0xffff0000, v183
	v_lshlrev_b32_e32 v222, 16, v184
	v_and_b32_e32 v223, 0xffff0000, v184
	v_lshlrev_b32_e32 v224, 16, v185
	v_and_b32_e32 v225, 0xffff0000, v185
	v_pk_mul_f32 v[218:219], v[110:111], v[218:219]
	v_pk_mul_f32 v[220:221], v[112:113], v[220:221]
	v_pk_mul_f32 v[222:223], v[106:107], v[222:223]
	v_pk_mul_f32 v[224:225], v[108:109], v[224:225]
	v_lshlrev_b32_e32 v182, 16, v150
	v_and_b32_e32 v183, 0xffff0000, v150
	v_pk_add_f32 v[218:219], v[218:219], v[182:183]
	v_lshlrev_b32_e32 v184, 16, v151
	v_and_b32_e32 v185, 0xffff0000, v151
	v_pk_add_f32 v[220:221], v[220:221], v[184:185]
	v_lshlrev_b32_e32 v182, 16, v152
	v_and_b32_e32 v183, 0xffff0000, v152
	v_pk_add_f32 v[222:223], v[222:223], v[182:183]
	v_lshlrev_b32_e32 v184, 16, v153
	v_and_b32_e32 v185, 0xffff0000, v153
	v_pk_add_f32 v[224:225], v[224:225], v[184:185]
	v_cvt_pk_bf16_f32 v218, v218, v219
	v_cvt_pk_bf16_f32 v219, v220, v221
	v_cvt_pk_bf16_f32 v220, v222, v223
	v_cvt_pk_bf16_f32 v221, v224, v225
	global_store_dwordx4 v[252:253], v[218:221], off offset:1024
	v_lshl_add_u64 v[182:183], v[252:253], 0, s[22:23]
	v_lshl_add_u64 v[150:151], v[252:253], 0, s[100:101]
	global_load_dwordx4 v[182:185], v[182:183], off offset:1024
	global_load_dwordx4 v[150:153], v[150:151], off offset:1024
	s_branch .Lmo_h1e_2
.Lmo_h1nm_2:
	v_lshlrev_b32_e32 v218, 16, v182
	v_and_b32_e32 v219, 0xffff0000, v182
	v_lshlrev_b32_e32 v220, 16, v183
	v_and_b32_e32 v221, 0xffff0000, v183
	v_lshlrev_b32_e32 v222, 16, v184
	v_and_b32_e32 v223, 0xffff0000, v184
	v_lshlrev_b32_e32 v224, 16, v185
	v_and_b32_e32 v225, 0xffff0000, v185
	v_pk_mul_f32 v[218:219], v[110:111], v[218:219]
	v_pk_mul_f32 v[220:221], v[112:113], v[220:221]
	v_pk_mul_f32 v[222:223], v[106:107], v[222:223]
	v_pk_mul_f32 v[224:225], v[108:109], v[224:225]
	v_cvt_pk_bf16_f32 v218, v218, v219
	v_cvt_pk_bf16_f32 v219, v220, v221
	v_cvt_pk_bf16_f32 v220, v222, v223
	v_cvt_pk_bf16_f32 v221, v224, v225
	global_store_dwordx4 v[252:253], v[218:221], off offset:1024
	v_lshl_add_u64 v[182:183], v[252:253], 0, s[22:23]
	s_nop 0
	global_load_dwordx4 v[182:185], v[182:183], off offset:1024
.Lmo_h1e_2:
	s_and_b64 vcc, exec, s[44:45]
	s_cbranch_vccnz .Lmo_h1nm_3
	v_lshlrev_b32_e32 v218, 16, v178
	v_and_b32_e32 v219, 0xffff0000, v178
	v_lshlrev_b32_e32 v220, 16, v179
	v_and_b32_e32 v221, 0xffff0000, v179
	v_lshlrev_b32_e32 v222, 16, v180
	v_and_b32_e32 v223, 0xffff0000, v180
	v_lshlrev_b32_e32 v224, 16, v181
	v_and_b32_e32 v225, 0xffff0000, v181
	v_pk_mul_f32 v[218:219], v[102:103], v[218:219]
	v_pk_mul_f32 v[220:221], v[104:105], v[220:221]
	v_pk_mul_f32 v[222:223], v[98:99], v[222:223]
	v_pk_mul_f32 v[224:225], v[100:101], v[224:225]
	v_lshlrev_b32_e32 v178, 16, v146
	v_and_b32_e32 v179, 0xffff0000, v146
	v_pk_add_f32 v[218:219], v[218:219], v[178:179]
	v_lshlrev_b32_e32 v180, 16, v147
	v_and_b32_e32 v181, 0xffff0000, v147
	v_pk_add_f32 v[220:221], v[220:221], v[180:181]
	v_lshlrev_b32_e32 v178, 16, v148
	v_and_b32_e32 v179, 0xffff0000, v148
	v_pk_add_f32 v[222:223], v[222:223], v[178:179]
	v_lshlrev_b32_e32 v180, 16, v149
	v_and_b32_e32 v181, 0xffff0000, v149
	v_pk_add_f32 v[224:225], v[224:225], v[180:181]
	v_cvt_pk_bf16_f32 v218, v218, v219
	v_cvt_pk_bf16_f32 v219, v220, v221
	v_cvt_pk_bf16_f32 v220, v222, v223
	v_cvt_pk_bf16_f32 v221, v224, v225
	global_store_dwordx4 v[252:253], v[218:221], off offset:1280
	v_lshl_add_u64 v[178:179], v[252:253], 0, s[22:23]
	v_lshl_add_u64 v[146:147], v[252:253], 0, s[100:101]
	global_load_dwordx4 v[178:181], v[178:179], off offset:1280
	global_load_dwordx4 v[146:149], v[146:147], off offset:1280
	s_branch .Lmo_h1e_3
; DI unsigned cvtpk(float lo, float hi) { typedef float f2 __attribute__((ext_vector_type(2))); typedef __bf16 b2 __attribute__((ext_vector_type(2))); f2 v = {lo, hi}; b2 b = __builtin_convertvector(v, b2); return __builtin_bit_cast(unsigned, b); }
; DI float bflo(unsigned w) { return __uint_as_float(w << 16); }
; DI float bfhi(unsigned w) { return __uint_as_float(w & 0xffff0000u); }
;     DI void operator()(f32x4 (&acc)[2][2][4][2], const pg8::GUnit& u, int wr, int wc, int fr, int fq) const {
;     ...
;                 for (int m = 0; m < 4; ++m) { bf16_t* mp = act + (size_t)(row0 + ai * 128 + m * 16) * PITCH + C_MERGED + col0;
; #pragma unroll
;                     for (int bj = 0; bj < 2; ++bj) {
;                         const u32x4 g = gq[m][bj];
;                         const f32x4 a0 = acc[ai][bj][m][0], a1 = acc[ai][bj][m][1];
;                         float r0 = bflo(g.x) * a0[0], r1 = bfhi(g.x) * a0[1], r2 = bflo(g.y) * a0[2], r3 = bfhi(g.y) * a0[3];
;                         float r4 = bflo(g.z) * a1[0], r5 = bfhi(g.z) * a1[1], r6 = bflo(g.w) * a1[2], r7 = bfhi(g.w) * a1[3];
;                         if (z > 1) { const u32x4 pm_ = mq[m][bj];
;                             r0 += bflo(pm_.x); r1 += bfhi(pm_.x); r2 += bflo(pm_.y); r3 += bfhi(pm_.y); r4 += bflo(pm_.z); r5 += bfhi(pm_.z); r6 += bflo(pm_.w); r7 += bfhi(pm_.w); }
;                         u32x4 w; w.x = cvtpk(r0, r1); w.y = cvtpk(r2, r3); w.z = cvtpk(r4, r5); w.w = cvtpk(r6, r7);
;                         *(u32x4*)(mp + bj * 128) = w;
;                     } }
.Lmo_h1nm_3:
	v_lshlrev_b32_e32 v218, 16, v178
	v_and_b32_e32 v219, 0xffff0000, v178
	v_lshlrev_b32_e32 v220, 16, v179
	v_and_b32_e32 v221, 0xffff0000, v179
	v_lshlrev_b32_e32 v222, 16, v180
	v_and_b32_e32 v223, 0xffff0000, v180
	v_lshlrev_b32_e32 v224, 16, v181
	v_and_b32_e32 v225, 0xffff0000, v181
	v_pk_mul_f32 v[218:219], v[102:103], v[218:219]
	v_pk_mul_f32 v[220:221], v[104:105], v[220:221]
	v_pk_mul_f32 v[222:223], v[98:99], v[222:223]
	v_pk_mul_f32 v[224:225], v[100:101], v[224:225]
	v_cvt_pk_bf16_f32 v218, v218, v219
	v_cvt_pk_bf16_f32 v219, v220, v221
	v_cvt_pk_bf16_f32 v220, v222, v223
	v_cvt_pk_bf16_f32 v221, v224, v225
	global_store_dwordx4 v[252:253], v[218:221], off offset:1280
	v_lshl_add_u64 v[178:179], v[252:253], 0, s[22:23]
	s_nop 0
	global_load_dwordx4 v[178:181], v[178:179], off offset:1280
.Lmo_h1e_3:
	v_lshl_add_u64 v[252:253], v[252:253], 0, s[98:99]
	s_and_b64 vcc, exec, s[44:45]
	s_cbranch_vccnz .Lmo_h1nm_4
	v_lshlrev_b32_e32 v218, 16, v174
	v_and_b32_e32 v219, 0xffff0000, v174
	v_lshlrev_b32_e32 v220, 16, v175
	v_and_b32_e32 v221, 0xffff0000, v175
	v_lshlrev_b32_e32 v222, 16, v176
	v_and_b32_e32 v223, 0xffff0000, v176
	v_lshlrev_b32_e32 v224, 16, v177
	v_and_b32_e32 v225, 0xffff0000, v177
	v_pk_mul_f32 v[218:219], v[94:95], v[218:219]
	v_pk_mul_f32 v[220:221], v[96:97], v[220:221]
	v_pk_mul_f32 v[222:223], v[90:91], v[222:223]
	v_pk_mul_f32 v[224:225], v[92:93], v[224:225]
	v_lshlrev_b32_e32 v174, 16, v142
	v_and_b32_e32 v175, 0xffff0000, v142
	v_pk_add_f32 v[218:219], v[218:219], v[174:175]
	v_lshlrev_b32_e32 v176, 16, v143
	v_and_b32_e32 v177, 0xffff0000, v143
	v_pk_add_f32 v[220:221], v[220:221], v[176:177]
	v_lshlrev_b32_e32 v174, 16, v144
	v_and_b32_e32 v175, 0xffff0000, v144
	v_pk_add_f32 v[222:223], v[222:223], v[174:175]
	v_lshlrev_b32_e32 v176, 16, v145
	v_and_b32_e32 v177, 0xffff0000, v145
	v_pk_add_f32 v[224:225], v[224:225], v[176:177]
	v_cvt_pk_bf16_f32 v218, v218, v219
	v_cvt_pk_bf16_f32 v219, v220, v221
	v_cvt_pk_bf16_f32 v220, v222, v223
	v_cvt_pk_bf16_f32 v221, v224, v225
	global_store_dwordx4 v[252:253], v[218:221], off offset:1024
	v_lshl_add_u64 v[174:175], v[252:253], 0, s[22:23]
	v_lshl_add_u64 v[142:143], v[252:253], 0, s[100:101]
	global_load_dwordx4 v[174:177], v[174:175], off offset:1024
	global_load_dwordx4 v[142:145], v[142:143], off offset:1024
	s_branch .Lmo_h1e_4
.Lmo_h1nm_4:
	v_lshlrev_b32_e32 v218, 16, v174
	v_and_b32_e32 v219, 0xffff0000, v174
	v_lshlrev_b32_e32 v220, 16, v175
	v_and_b32_e32 v221, 0xffff0000, v175
	v_lshlrev_b32_e32 v222, 16, v176
	v_and_b32_e32 v223, 0xffff0000, v176
	v_lshlrev_b32_e32 v224, 16, v177
	v_and_b32_e32 v225, 0xffff0000, v177
	v_pk_mul_f32 v[218:219], v[94:95], v[218:219]
	v_pk_mul_f32 v[220:221], v[96:97], v[220:221]
	v_pk_mul_f32 v[222:223], v[90:91], v[222:223]
	v_pk_mul_f32 v[224:225], v[92:93], v[224:225]
	v_cvt_pk_bf16_f32 v218, v218, v219
	v_cvt_pk_bf16_f32 v219, v220, v221
	v_cvt_pk_bf16_f32 v220, v222, v223
	v_cvt_pk_bf16_f32 v221, v224, v225
	global_store_dwordx4 v[252:253], v[218:221], off offset:1024
	v_lshl_add_u64 v[174:175], v[252:253], 0, s[22:23]
	s_nop 0
	global_load_dwordx4 v[174:177], v[174:175], off offset:1024
.Lmo_h1e_4:
	s_and_b64 vcc, exec, s[44:45]
	s_cbranch_vccnz .Lmo_h1nm_5
	v_lshlrev_b32_e32 v218, 16, v170
	v_and_b32_e32 v219, 0xffff0000, v170
	v_lshlrev_b32_e32 v220, 16, v171
	v_and_b32_e32 v221, 0xffff0000, v171
	v_lshlrev_b32_e32 v222, 16, v172
	v_and_b32_e32 v223, 0xffff0000, v172
	v_lshlrev_b32_e32 v224, 16, v173
	v_and_b32_e32 v225, 0xffff0000, v173
	v_pk_mul_f32 v[218:219], v[86:87], v[218:219]
	v_pk_mul_f32 v[220:221], v[88:89], v[220:221]
	v_pk_mul_f32 v[222:223], v[82:83], v[222:223]
	v_pk_mul_f32 v[224:225], v[84:85], v[224:225]
	v_lshlrev_b32_e32 v170, 16, v138
	v_and_b32_e32 v171, 0xffff0000, v138
	v_pk_add_f32 v[218:219], v[218:219], v[170:171]
	v_lshlrev_b32_e32 v172, 16, v139
	v_and_b32_e32 v173, 0xffff0000, v139
	v_pk_add_f32 v[220:221], v[220:221], v[172:173]
	v_lshlrev_b32_e32 v170, 16, v140
	v_and_b32_e32 v171, 0xffff0000, v140
	v_pk_add_f32 v[222:223], v[222:223], v[170:171]
	v_lshlrev_b32_e32 v172, 16, v141
	v_and_b32_e32 v173, 0xffff0000, v141
	v_pk_add_f32 v[224:225], v[224:225], v[172:173]
	v_cvt_pk_bf16_f32 v218, v218, v219
	v_cvt_pk_bf16_f32 v219, v220, v221
	v_cvt_pk_bf16_f32 v220, v222, v223
	v_cvt_pk_bf16_f32 v221, v224, v225
	global_store_dwordx4 v[252:253], v[218:221], off offset:1280
	v_lshl_add_u64 v[170:171], v[252:253], 0, s[22:23]
	v_lshl_add_u64 v[138:139], v[252:253], 0, s[100:101]
	global_load_dwordx4 v[170:173], v[170:171], off offset:1280
	global_load_dwordx4 v[138:141], v[138:139], off offset:1280
	s_branch .Lmo_h1e_5
.Lmo_h1nm_5:
	v_lshlrev_b32_e32 v218, 16, v170
	v_and_b32_e32 v219, 0xffff0000, v170
	v_lshlrev_b32_e32 v220, 16, v171
	v_and_b32_e32 v221, 0xffff0000, v171
	v_lshlrev_b32_e32 v222, 16, v172
	v_and_b32_e32 v223, 0xffff0000, v172
	v_lshlrev_b32_e32 v224, 16, v173
	v_and_b32_e32 v225, 0xffff0000, v173
	v_pk_mul_f32 v[218:219], v[86:87], v[218:219]
	v_pk_mul_f32 v[220:221], v[88:89], v[220:221]
	v_pk_mul_f32 v[222:223], v[82:83], v[222:223]
	v_pk_mul_f32 v[224:225], v[84:85], v[224:225]
	v_cvt_pk_bf16_f32 v218, v218, v219
	v_cvt_pk_bf16_f32 v219, v220, v221
	v_cvt_pk_bf16_f32 v220, v222, v223
	v_cvt_pk_bf16_f32 v221, v224, v225
	global_store_dwordx4 v[252:253], v[218:221], off offset:1280
	v_lshl_add_u64 v[170:171], v[252:253], 0, s[22:23]
	s_nop 0
	global_load_dwordx4 v[170:173], v[170:171], off offset:1280
; DI unsigned cvtpk(float lo, float hi) { typedef float f2 __attribute__((ext_vector_type(2))); typedef __bf16 b2 __attribute__((ext_vector_type(2))); f2 v = {lo, hi}; b2 b = __builtin_convertvector(v, b2); return __builtin_bit_cast(unsigned, b); }
; DI float bflo(unsigned w) { return __uint_as_float(w << 16); }
; DI float bfhi(unsigned w) { return __uint_as_float(w & 0xffff0000u); }
;     DI void operator()(f32x4 (&acc)[2][2][4][2], const pg8::GUnit& u, int wr, int wc, int fr, int fq) const {
;     ...
;                 for (int m = 0; m < 4; ++m) { bf16_t* mp = act + (size_t)(row0 + ai * 128 + m * 16) * PITCH + C_MERGED + col0;
; #pragma unroll
;                     for (int bj = 0; bj < 2; ++bj) {
;                         const u32x4 g = gq[m][bj];
;                         const f32x4 a0 = acc[ai][bj][m][0], a1 = acc[ai][bj][m][1];
;                         float r0 = bflo(g.x) * a0[0], r1 = bfhi(g.x) * a0[1], r2 = bflo(g.y) * a0[2], r3 = bfhi(g.y) * a0[3];
;                         float r4 = bflo(g.z) * a1[0], r5 = bfhi(g.z) * a1[1], r6 = bflo(g.w) * a1[2], r7 = bfhi(g.w) * a1[3];
;                         if (z > 1) { const u32x4 pm_ = mq[m][bj];
;                             r0 += bflo(pm_.x); r1 += bfhi(pm_.x); r2 += bflo(pm_.y); r3 += bfhi(pm_.y); r4 += bflo(pm_.z); r5 += bfhi(pm_.z); r6 += bflo(pm_.w); r7 += bfhi(pm_.w); }
;                         u32x4 w; w.x = cvtpk(r0, r1); w.y = cvtpk(r2, r3); w.z = cvtpk(r4, r5); w.w = cvtpk(r6, r7);
;                         *(u32x4*)(mp + bj * 128) = w;
;                     } }
.Lmo_h1e_5:
	v_lshl_add_u64 v[252:253], v[252:253], 0, s[98:99]
	s_and_b64 vcc, exec, s[44:45]
	s_cbranch_vccnz .Lmo_h1nm_6
	v_lshlrev_b32_e32 v218, 16, v166
	v_and_b32_e32 v219, 0xffff0000, v166
	v_lshlrev_b32_e32 v220, 16, v167
	v_and_b32_e32 v221, 0xffff0000, v167
	v_lshlrev_b32_e32 v222, 16, v168
	v_and_b32_e32 v223, 0xffff0000, v168
	v_lshlrev_b32_e32 v224, 16, v169
	v_and_b32_e32 v225, 0xffff0000, v169
	v_pk_mul_f32 v[218:219], v[78:79], v[218:219]
	v_pk_mul_f32 v[220:221], v[80:81], v[220:221]
	v_pk_mul_f32 v[222:223], v[74:75], v[222:223]
	v_pk_mul_f32 v[224:225], v[76:77], v[224:225]
	v_lshlrev_b32_e32 v166, 16, v134
	v_and_b32_e32 v167, 0xffff0000, v134
	v_pk_add_f32 v[218:219], v[218:219], v[166:167]
	v_lshlrev_b32_e32 v168, 16, v135
	v_and_b32_e32 v169, 0xffff0000, v135
	v_pk_add_f32 v[220:221], v[220:221], v[168:169]
	v_lshlrev_b32_e32 v166, 16, v136
	v_and_b32_e32 v167, 0xffff0000, v136
	v_pk_add_f32 v[222:223], v[222:223], v[166:167]
	v_lshlrev_b32_e32 v168, 16, v137
	v_and_b32_e32 v169, 0xffff0000, v137
	v_pk_add_f32 v[224:225], v[224:225], v[168:169]
	v_cvt_pk_bf16_f32 v218, v218, v219
	v_cvt_pk_bf16_f32 v219, v220, v221
	v_cvt_pk_bf16_f32 v220, v222, v223
	v_cvt_pk_bf16_f32 v221, v224, v225
	global_store_dwordx4 v[252:253], v[218:221], off offset:1024
	v_lshl_add_u64 v[166:167], v[252:253], 0, s[22:23]
	v_lshl_add_u64 v[134:135], v[252:253], 0, s[100:101]
	global_load_dwordx4 v[166:169], v[166:167], off offset:1024
	global_load_dwordx4 v[134:137], v[134:135], off offset:1024
	s_branch .Lmo_h1e_6
.Lmo_h1nm_6:
	v_lshlrev_b32_e32 v218, 16, v166
	v_and_b32_e32 v219, 0xffff0000, v166
	v_lshlrev_b32_e32 v220, 16, v167
	v_and_b32_e32 v221, 0xffff0000, v167
	v_lshlrev_b32_e32 v222, 16, v168
	v_and_b32_e32 v223, 0xffff0000, v168
	v_lshlrev_b32_e32 v224, 16, v169
	v_and_b32_e32 v225, 0xffff0000, v169
	v_pk_mul_f32 v[218:219], v[78:79], v[218:219]
	v_pk_mul_f32 v[220:221], v[80:81], v[220:221]
	v_pk_mul_f32 v[222:223], v[74:75], v[222:223]
	v_pk_mul_f32 v[224:225], v[76:77], v[224:225]
	v_cvt_pk_bf16_f32 v218, v218, v219
	v_cvt_pk_bf16_f32 v219, v220, v221
	v_cvt_pk_bf16_f32 v220, v222, v223
	v_cvt_pk_bf16_f32 v221, v224, v225
	global_store_dwordx4 v[252:253], v[218:221], off offset:1024
	v_lshl_add_u64 v[166:167], v[252:253], 0, s[22:23]
	s_nop 0
	global_load_dwordx4 v[166:169], v[166:167], off offset:1024
.Lmo_h1e_6:
	s_and_b64 vcc, exec, s[44:45]
	s_cbranch_vccnz .Lmo_h1nm_7
	v_lshlrev_b32_e32 v218, 16, v162
	v_and_b32_e32 v219, 0xffff0000, v162
	v_lshlrev_b32_e32 v220, 16, v163
	v_and_b32_e32 v221, 0xffff0000, v163
	v_lshlrev_b32_e32 v222, 16, v164
	v_and_b32_e32 v223, 0xffff0000, v164
	v_lshlrev_b32_e32 v224, 16, v165
	v_and_b32_e32 v225, 0xffff0000, v165
	v_pk_mul_f32 v[218:219], v[70:71], v[218:219]
	v_pk_mul_f32 v[220:221], v[72:73], v[220:221]
	v_pk_mul_f32 v[222:223], v[66:67], v[222:223]
	v_pk_mul_f32 v[224:225], v[68:69], v[224:225]
	v_lshlrev_b32_e32 v162, 16, v130
	v_and_b32_e32 v163, 0xffff0000, v130
	v_pk_add_f32 v[218:219], v[218:219], v[162:163]
	v_lshlrev_b32_e32 v164, 16, v131
	v_and_b32_e32 v165, 0xffff0000, v131
	v_pk_add_f32 v[220:221], v[220:221], v[164:165]
	v_lshlrev_b32_e32 v162, 16, v132
	v_and_b32_e32 v163, 0xffff0000, v132
	v_pk_add_f32 v[222:223], v[222:223], v[162:163]
	v_lshlrev_b32_e32 v164, 16, v133
	v_and_b32_e32 v165, 0xffff0000, v133
	v_pk_add_f32 v[224:225], v[224:225], v[164:165]
	v_cvt_pk_bf16_f32 v218, v218, v219
	v_cvt_pk_bf16_f32 v219, v220, v221
	v_cvt_pk_bf16_f32 v220, v222, v223
	v_cvt_pk_bf16_f32 v221, v224, v225
	global_store_dwordx4 v[252:253], v[218:221], off offset:1280
	v_lshl_add_u64 v[162:163], v[252:253], 0, s[22:23]
	v_lshl_add_u64 v[130:131], v[252:253], 0, s[100:101]
	global_load_dwordx4 v[162:165], v[162:163], off offset:1280
	global_load_dwordx4 v[130:133], v[130:131], off offset:1280
	s_branch .Lmo_h1e_7
.Lmo_h1nm_7:
	v_lshlrev_b32_e32 v218, 16, v162
	v_and_b32_e32 v219, 0xffff0000, v162
	v_lshlrev_b32_e32 v220, 16, v163
	v_and_b32_e32 v221, 0xffff0000, v163
	v_lshlrev_b32_e32 v222, 16, v164
	v_and_b32_e32 v223, 0xffff0000, v164
	v_lshlrev_b32_e32 v224, 16, v165
	v_and_b32_e32 v225, 0xffff0000, v165
	v_pk_mul_f32 v[218:219], v[70:71], v[218:219]
	v_pk_mul_f32 v[220:221], v[72:73], v[220:221]
	v_pk_mul_f32 v[222:223], v[66:67], v[222:223]
	v_pk_mul_f32 v[224:225], v[68:69], v[224:225]
	v_cvt_pk_bf16_f32 v218, v218, v219
	v_cvt_pk_bf16_f32 v219, v220, v221
	v_cvt_pk_bf16_f32 v220, v222, v223
	v_cvt_pk_bf16_f32 v221, v224, v225
	global_store_dwordx4 v[252:253], v[218:221], off offset:1280
	v_lshl_add_u64 v[162:163], v[252:253], 0, s[22:23]
	s_nop 0
	global_load_dwordx4 v[162:165], v[162:163], off offset:1280
.Lmo_h1e_7:
	s_mul_i32 s100, s31, 0x50
	s_nop 0
	v_lshl_add_u64 v[252:253], v[252:253], 0, s[100:101]
	s_and_b64 vcc, exec, s[44:45]
	s_cbranch_vccnz .Lmo_h2nm_0
	s_waitcnt vmcnt(21)
	v_lshlrev_b32_e32 v218, 16, v190
	v_and_b32_e32 v219, 0xffff0000, v190
	v_lshlrev_b32_e32 v220, 16, v191
	v_and_b32_e32 v221, 0xffff0000, v191
	v_lshlrev_b32_e32 v222, 16, v192
	v_and_b32_e32 v223, 0xffff0000, v192
	v_lshlrev_b32_e32 v224, 16, v193
	v_and_b32_e32 v225, 0xffff0000, v193
	v_pk_mul_f32 v[218:219], v[62:63], v[218:219]
	v_pk_mul_f32 v[220:221], v[64:65], v[220:221]
	v_pk_mul_f32 v[222:223], v[58:59], v[222:223]
	v_pk_mul_f32 v[224:225], v[60:61], v[224:225]
	v_lshlrev_b32_e32 v190, 16, v158
	v_and_b32_e32 v191, 0xffff0000, v158
	v_pk_add_f32 v[218:219], v[218:219], v[190:191]
	v_lshlrev_b32_e32 v192, 16, v159
	v_and_b32_e32 v193, 0xffff0000, v159
	v_pk_add_f32 v[220:221], v[220:221], v[192:193]
	v_lshlrev_b32_e32 v190, 16, v160
	v_and_b32_e32 v191, 0xffff0000, v160
	v_pk_add_f32 v[222:223], v[222:223], v[190:191]
	v_lshlrev_b32_e32 v192, 16, v161
	v_and_b32_e32 v193, 0xffff0000, v161
	v_pk_add_f32 v[224:225], v[224:225], v[192:193]
	s_branch .Lmo_h2e_0
; DI unsigned cvtpk(float lo, float hi) { typedef float f2 __attribute__((ext_vector_type(2))); typedef __bf16 b2 __attribute__((ext_vector_type(2))); f2 v = {lo, hi}; b2 b = __builtin_convertvector(v, b2); return __builtin_bit_cast(unsigned, b); }
; DI float bflo(unsigned w) { return __uint_as_float(w << 16); }
; DI float bfhi(unsigned w) { return __uint_as_float(w & 0xffff0000u); }
;     DI void operator()(f32x4 (&acc)[2][2][4][2], const pg8::GUnit& u, int wr, int wc, int fr, int fq) const {
;     ...
;                 for (int m = 0; m < 4; ++m) { bf16_t* mp = act + (size_t)(row0 + ai * 128 + m * 16) * PITCH + C_MERGED + col0;
; #pragma unroll
;                     for (int bj = 0; bj < 2; ++bj) {
;                         const u32x4 g = gq[m][bj];
;                         const f32x4 a0 = acc[ai][bj][m][0], a1 = acc[ai][bj][m][1];
;                         float r0 = bflo(g.x) * a0[0], r1 = bfhi(g.x) * a0[1], r2 = bflo(g.y) * a0[2], r3 = bfhi(g.y) * a0[3];
;                         float r4 = bflo(g.z) * a1[0], r5 = bfhi(g.z) * a1[1], r6 = bflo(g.w) * a1[2], r7 = bfhi(g.w) * a1[3];
;                         if (z > 1) { const u32x4 pm_ = mq[m][bj];
;                             r0 += bflo(pm_.x); r1 += bfhi(pm_.x); r2 += bflo(pm_.y); r3 += bfhi(pm_.y); r4 += bflo(pm_.z); r5 += bfhi(pm_.z); r6 += bflo(pm_.w); r7 += bfhi(pm_.w); }
;                         u32x4 w; w.x = cvtpk(r0, r1); w.y = cvtpk(r2, r3); w.z = cvtpk(r4, r5); w.w = cvtpk(r6, r7);
;                         *(u32x4*)(mp + bj * 128) = w;
;                     } }
.Lmo_h2nm_0:
	s_waitcnt vmcnt(14)
	v_lshlrev_b32_e32 v218, 16, v190
	v_and_b32_e32 v219, 0xffff0000, v190
	v_lshlrev_b32_e32 v220, 16, v191
	v_and_b32_e32 v221, 0xffff0000, v191
	v_lshlrev_b32_e32 v222, 16, v192
	v_and_b32_e32 v223, 0xffff0000, v192
	v_lshlrev_b32_e32 v224, 16, v193
	v_and_b32_e32 v225, 0xffff0000, v193
	v_pk_mul_f32 v[218:219], v[62:63], v[218:219]
	v_pk_mul_f32 v[220:221], v[64:65], v[220:221]
	v_pk_mul_f32 v[222:223], v[58:59], v[222:223]
	v_pk_mul_f32 v[224:225], v[60:61], v[224:225]
.Lmo_h2e_0:
	v_cvt_pk_bf16_f32 v218, v218, v219
	v_cvt_pk_bf16_f32 v219, v220, v221
	v_cvt_pk_bf16_f32 v220, v222, v223
	v_cvt_pk_bf16_f32 v221, v224, v225
	global_store_dwordx4 v[252:253], v[218:221], off offset:1024
	s_nop 1
	s_and_b64 vcc, exec, s[44:45]
	s_cbranch_vccnz .Lmo_h2nm_1
	s_waitcnt vmcnt(19)
	v_lshlrev_b32_e32 v218, 16, v186
	v_and_b32_e32 v219, 0xffff0000, v186
	v_lshlrev_b32_e32 v220, 16, v187
	v_and_b32_e32 v221, 0xffff0000, v187
	v_lshlrev_b32_e32 v222, 16, v188
	v_and_b32_e32 v223, 0xffff0000, v188
	v_lshlrev_b32_e32 v224, 16, v189
	v_and_b32_e32 v225, 0xffff0000, v189
	v_pk_mul_f32 v[218:219], v[54:55], v[218:219]
	v_pk_mul_f32 v[220:221], v[56:57], v[220:221]
	v_pk_mul_f32 v[222:223], v[50:51], v[222:223]
	v_pk_mul_f32 v[224:225], v[52:53], v[224:225]
	v_lshlrev_b32_e32 v186, 16, v154
	v_and_b32_e32 v187, 0xffff0000, v154
	v_pk_add_f32 v[218:219], v[218:219], v[186:187]
	v_lshlrev_b32_e32 v188, 16, v155
	v_and_b32_e32 v189, 0xffff0000, v155
	v_pk_add_f32 v[220:221], v[220:221], v[188:189]
	v_lshlrev_b32_e32 v186, 16, v156
	v_and_b32_e32 v187, 0xffff0000, v156
	v_pk_add_f32 v[222:223], v[222:223], v[186:187]
	v_lshlrev_b32_e32 v188, 16, v157
	v_and_b32_e32 v189, 0xffff0000, v157
	v_pk_add_f32 v[224:225], v[224:225], v[188:189]
	s_branch .Lmo_h2e_1
.Lmo_h2nm_1:
	s_waitcnt vmcnt(13)
	v_lshlrev_b32_e32 v218, 16, v186
	v_and_b32_e32 v219, 0xffff0000, v186
	v_lshlrev_b32_e32 v220, 16, v187
	v_and_b32_e32 v221, 0xffff0000, v187
	v_lshlrev_b32_e32 v222, 16, v188
	v_and_b32_e32 v223, 0xffff0000, v188
	v_lshlrev_b32_e32 v224, 16, v189
	v_and_b32_e32 v225, 0xffff0000, v189
	v_pk_mul_f32 v[218:219], v[54:55], v[218:219]
	v_pk_mul_f32 v[220:221], v[56:57], v[220:221]
	v_pk_mul_f32 v[222:223], v[50:51], v[222:223]
	v_pk_mul_f32 v[224:225], v[52:53], v[224:225]
.Lmo_h2e_1:
	v_cvt_pk_bf16_f32 v218, v218, v219
	v_cvt_pk_bf16_f32 v219, v220, v221
	v_cvt_pk_bf16_f32 v220, v222, v223
	v_cvt_pk_bf16_f32 v221, v224, v225
	global_store_dwordx4 v[252:253], v[218:221], off offset:1280
	v_lshl_add_u64 v[252:253], v[252:253], 0, s[98:99]
	s_and_b64 vcc, exec, s[44:45]
	s_cbranch_vccnz .Lmo_h2nm_2
	s_waitcnt vmcnt(17)
	v_lshlrev_b32_e32 v218, 16, v182
	v_and_b32_e32 v219, 0xffff0000, v182
	v_lshlrev_b32_e32 v220, 16, v183
	v_and_b32_e32 v221, 0xffff0000, v183
	v_lshlrev_b32_e32 v222, 16, v184
	v_and_b32_e32 v223, 0xffff0000, v184
	v_lshlrev_b32_e32 v224, 16, v185
	v_and_b32_e32 v225, 0xffff0000, v185
	v_pk_mul_f32 v[218:219], v[46:47], v[218:219]
	v_pk_mul_f32 v[220:221], v[48:49], v[220:221]
	v_pk_mul_f32 v[222:223], v[42:43], v[222:223]
	v_pk_mul_f32 v[224:225], v[44:45], v[224:225]
	v_lshlrev_b32_e32 v182, 16, v150
	v_and_b32_e32 v183, 0xffff0000, v150
	v_pk_add_f32 v[218:219], v[218:219], v[182:183]
	v_lshlrev_b32_e32 v184, 16, v151
	v_and_b32_e32 v185, 0xffff0000, v151
	v_pk_add_f32 v[220:221], v[220:221], v[184:185]
	v_lshlrev_b32_e32 v182, 16, v152
	v_and_b32_e32 v183, 0xffff0000, v152
	v_pk_add_f32 v[222:223], v[222:223], v[182:183]
	v_lshlrev_b32_e32 v184, 16, v153
	v_and_b32_e32 v185, 0xffff0000, v153
	v_pk_add_f32 v[224:225], v[224:225], v[184:185]
	s_branch .Lmo_h2e_2
.Lmo_h2nm_2:
	s_waitcnt vmcnt(12)
	v_lshlrev_b32_e32 v218, 16, v182
	v_and_b32_e32 v219, 0xffff0000, v182
	v_lshlrev_b32_e32 v220, 16, v183
	v_and_b32_e32 v221, 0xffff0000, v183
	v_lshlrev_b32_e32 v222, 16, v184
	v_and_b32_e32 v223, 0xffff0000, v184
	v_lshlrev_b32_e32 v224, 16, v185
	v_and_b32_e32 v225, 0xffff0000, v185
	v_pk_mul_f32 v[218:219], v[46:47], v[218:219]
	v_pk_mul_f32 v[220:221], v[48:49], v[220:221]
	v_pk_mul_f32 v[222:223], v[42:43], v[222:223]
	v_pk_mul_f32 v[224:225], v[44:45], v[224:225]
.Lmo_h2e_2:
	v_cvt_pk_bf16_f32 v218, v218, v219
	v_cvt_pk_bf16_f32 v219, v220, v221
	v_cvt_pk_bf16_f32 v220, v222, v223
	v_cvt_pk_bf16_f32 v221, v224, v225
	global_store_dwordx4 v[252:253], v[218:221], off offset:1024
	s_nop 1
	s_and_b64 vcc, exec, s[44:45]
	s_cbranch_vccnz .Lmo_h2nm_3
	s_waitcnt vmcnt(15)
	v_lshlrev_b32_e32 v218, 16, v178
	v_and_b32_e32 v219, 0xffff0000, v178
	v_lshlrev_b32_e32 v220, 16, v179
	v_and_b32_e32 v221, 0xffff0000, v179
	v_lshlrev_b32_e32 v222, 16, v180
	v_and_b32_e32 v223, 0xffff0000, v180
	v_lshlrev_b32_e32 v224, 16, v181
	v_and_b32_e32 v225, 0xffff0000, v181
	v_pk_mul_f32 v[218:219], v[38:39], v[218:219]
	v_pk_mul_f32 v[220:221], v[40:41], v[220:221]
	v_pk_mul_f32 v[222:223], v[34:35], v[222:223]
	v_pk_mul_f32 v[224:225], v[36:37], v[224:225]
	v_lshlrev_b32_e32 v178, 16, v146
	v_and_b32_e32 v179, 0xffff0000, v146
	v_pk_add_f32 v[218:219], v[218:219], v[178:179]
	v_lshlrev_b32_e32 v180, 16, v147
	v_and_b32_e32 v181, 0xffff0000, v147
	v_pk_add_f32 v[220:221], v[220:221], v[180:181]
	v_lshlrev_b32_e32 v178, 16, v148
	v_and_b32_e32 v179, 0xffff0000, v148
	v_pk_add_f32 v[222:223], v[222:223], v[178:179]
	v_lshlrev_b32_e32 v180, 16, v149
	v_and_b32_e32 v181, 0xffff0000, v149
	v_pk_add_f32 v[224:225], v[224:225], v[180:181]
	s_branch .Lmo_h2e_3
; DI unsigned cvtpk(float lo, float hi) { typedef float f2 __attribute__((ext_vector_type(2))); typedef __bf16 b2 __attribute__((ext_vector_type(2))); f2 v = {lo, hi}; b2 b = __builtin_convertvector(v, b2); return __builtin_bit_cast(unsigned, b); }
; DI float bflo(unsigned w) { return __uint_as_float(w << 16); }
; DI float bfhi(unsigned w) { return __uint_as_float(w & 0xffff0000u); }
;     DI void operator()(f32x4 (&acc)[2][2][4][2], const pg8::GUnit& u, int wr, int wc, int fr, int fq) const {
;     ...
;                 for (int m = 0; m < 4; ++m) { bf16_t* mp = act + (size_t)(row0 + ai * 128 + m * 16) * PITCH + C_MERGED + col0;
; #pragma unroll
;                     for (int bj = 0; bj < 2; ++bj) {
;                         const u32x4 g = gq[m][bj];
;                         const f32x4 a0 = acc[ai][bj][m][0], a1 = acc[ai][bj][m][1];
;                         float r0 = bflo(g.x) * a0[0], r1 = bfhi(g.x) * a0[1], r2 = bflo(g.y) * a0[2], r3 = bfhi(g.y) * a0[3];
;                         float r4 = bflo(g.z) * a1[0], r5 = bfhi(g.z) * a1[1], r6 = bflo(g.w) * a1[2], r7 = bfhi(g.w) * a1[3];
;                         if (z > 1) { const u32x4 pm_ = mq[m][bj];
;                             r0 += bflo(pm_.x); r1 += bfhi(pm_.x); r2 += bflo(pm_.y); r3 += bfhi(pm_.y); r4 += bflo(pm_.z); r5 += bfhi(pm_.z); r6 += bflo(pm_.w); r7 += bfhi(pm_.w); }
;                         u32x4 w; w.x = cvtpk(r0, r1); w.y = cvtpk(r2, r3); w.z = cvtpk(r4, r5); w.w = cvtpk(r6, r7);
;                         *(u32x4*)(mp + bj * 128) = w;
;                     } }
.Lmo_h2nm_3:
	s_waitcnt vmcnt(11)
	v_lshlrev_b32_e32 v218, 16, v178
	v_and_b32_e32 v219, 0xffff0000, v178
	v_lshlrev_b32_e32 v220, 16, v179
	v_and_b32_e32 v221, 0xffff0000, v179
	v_lshlrev_b32_e32 v222, 16, v180
	v_and_b32_e32 v223, 0xffff0000, v180
	v_lshlrev_b32_e32 v224, 16, v181
	v_and_b32_e32 v225, 0xffff0000, v181
	v_pk_mul_f32 v[218:219], v[38:39], v[218:219]
	v_pk_mul_f32 v[220:221], v[40:41], v[220:221]
	v_pk_mul_f32 v[222:223], v[34:35], v[222:223]
	v_pk_mul_f32 v[224:225], v[36:37], v[224:225]
.Lmo_h2e_3:
	v_cvt_pk_bf16_f32 v218, v218, v219
	v_cvt_pk_bf16_f32 v219, v220, v221
	v_cvt_pk_bf16_f32 v220, v222, v223
	v_cvt_pk_bf16_f32 v221, v224, v225
	global_store_dwordx4 v[252:253], v[218:221], off offset:1280
	v_lshl_add_u64 v[252:253], v[252:253], 0, s[98:99]
	s_and_b64 vcc, exec, s[44:45]
	s_cbranch_vccnz .Lmo_h2nm_4
	s_waitcnt vmcnt(13)
	v_lshlrev_b32_e32 v218, 16, v174
	v_and_b32_e32 v219, 0xffff0000, v174
	v_lshlrev_b32_e32 v220, 16, v175
	v_and_b32_e32 v221, 0xffff0000, v175
	v_lshlrev_b32_e32 v222, 16, v176
	v_and_b32_e32 v223, 0xffff0000, v176
	v_lshlrev_b32_e32 v224, 16, v177
	v_and_b32_e32 v225, 0xffff0000, v177
	v_pk_mul_f32 v[218:219], v[30:31], v[218:219]
	v_pk_mul_f32 v[220:221], v[32:33], v[220:221]
	v_pk_mul_f32 v[222:223], v[26:27], v[222:223]
	v_pk_mul_f32 v[224:225], v[28:29], v[224:225]
	v_lshlrev_b32_e32 v174, 16, v142
	v_and_b32_e32 v175, 0xffff0000, v142
	v_pk_add_f32 v[218:219], v[218:219], v[174:175]
	v_lshlrev_b32_e32 v176, 16, v143
	v_and_b32_e32 v177, 0xffff0000, v143
	v_pk_add_f32 v[220:221], v[220:221], v[176:177]
	v_lshlrev_b32_e32 v174, 16, v144
	v_and_b32_e32 v175, 0xffff0000, v144
	v_pk_add_f32 v[222:223], v[222:223], v[174:175]
	v_lshlrev_b32_e32 v176, 16, v145
	v_and_b32_e32 v177, 0xffff0000, v145
	v_pk_add_f32 v[224:225], v[224:225], v[176:177]
	s_branch .Lmo_h2e_4
.Lmo_h2nm_4:
	s_waitcnt vmcnt(10)
	v_lshlrev_b32_e32 v218, 16, v174
	v_and_b32_e32 v219, 0xffff0000, v174
	v_lshlrev_b32_e32 v220, 16, v175
	v_and_b32_e32 v221, 0xffff0000, v175
	v_lshlrev_b32_e32 v222, 16, v176
	v_and_b32_e32 v223, 0xffff0000, v176
	v_lshlrev_b32_e32 v224, 16, v177
	v_and_b32_e32 v225, 0xffff0000, v177
	v_pk_mul_f32 v[218:219], v[30:31], v[218:219]
	v_pk_mul_f32 v[220:221], v[32:33], v[220:221]
	v_pk_mul_f32 v[222:223], v[26:27], v[222:223]
	v_pk_mul_f32 v[224:225], v[28:29], v[224:225]
.Lmo_h2e_4:
	v_cvt_pk_bf16_f32 v218, v218, v219
	v_cvt_pk_bf16_f32 v219, v220, v221
	v_cvt_pk_bf16_f32 v220, v222, v223
	v_cvt_pk_bf16_f32 v221, v224, v225
	global_store_dwordx4 v[252:253], v[218:221], off offset:1024
	s_nop 1
	s_and_b64 vcc, exec, s[44:45]
	s_cbranch_vccnz .Lmo_h2nm_5
	s_waitcnt vmcnt(11)
	v_lshlrev_b32_e32 v218, 16, v170
	v_and_b32_e32 v219, 0xffff0000, v170
	v_lshlrev_b32_e32 v220, 16, v171
	v_and_b32_e32 v221, 0xffff0000, v171
	v_lshlrev_b32_e32 v222, 16, v172
	v_and_b32_e32 v223, 0xffff0000, v172
	v_lshlrev_b32_e32 v224, 16, v173
	v_and_b32_e32 v225, 0xffff0000, v173
	v_pk_mul_f32 v[218:219], v[22:23], v[218:219]
	v_pk_mul_f32 v[220:221], v[24:25], v[220:221]
	v_pk_mul_f32 v[222:223], v[18:19], v[222:223]
	v_pk_mul_f32 v[224:225], v[20:21], v[224:225]
	v_lshlrev_b32_e32 v170, 16, v138
	v_and_b32_e32 v171, 0xffff0000, v138
	v_pk_add_f32 v[218:219], v[218:219], v[170:171]
	v_lshlrev_b32_e32 v172, 16, v139
	v_and_b32_e32 v173, 0xffff0000, v139
	v_pk_add_f32 v[220:221], v[220:221], v[172:173]
	v_lshlrev_b32_e32 v170, 16, v140
	v_and_b32_e32 v171, 0xffff0000, v140
	v_pk_add_f32 v[222:223], v[222:223], v[170:171]
	v_lshlrev_b32_e32 v172, 16, v141
	v_and_b32_e32 v173, 0xffff0000, v141
	v_pk_add_f32 v[224:225], v[224:225], v[172:173]
	s_branch .Lmo_h2e_5
.Lmo_h2nm_5:
	s_waitcnt vmcnt(9)
	v_lshlrev_b32_e32 v218, 16, v170
	v_and_b32_e32 v219, 0xffff0000, v170
	v_lshlrev_b32_e32 v220, 16, v171
	v_and_b32_e32 v221, 0xffff0000, v171
	v_lshlrev_b32_e32 v222, 16, v172
	v_and_b32_e32 v223, 0xffff0000, v172
	v_lshlrev_b32_e32 v224, 16, v173
	v_and_b32_e32 v225, 0xffff0000, v173
	v_pk_mul_f32 v[218:219], v[22:23], v[218:219]
	v_pk_mul_f32 v[220:221], v[24:25], v[220:221]
	v_pk_mul_f32 v[222:223], v[18:19], v[222:223]
	v_pk_mul_f32 v[224:225], v[20:21], v[224:225]
; DI unsigned cvtpk(float lo, float hi) { typedef float f2 __attribute__((ext_vector_type(2))); typedef __bf16 b2 __attribute__((ext_vector_type(2))); f2 v = {lo, hi}; b2 b = __builtin_convertvector(v, b2); return __builtin_bit_cast(unsigned, b); }
; DI float bflo(unsigned w) { return __uint_as_float(w << 16); }
; DI float bfhi(unsigned w) { return __uint_as_float(w & 0xffff0000u); }
;     DI void operator()(f32x4 (&acc)[2][2][4][2], const pg8::GUnit& u, int wr, int wc, int fr, int fq) const {
;     ...
;                 for (int m = 0; m < 4; ++m) { bf16_t* mp = act + (size_t)(row0 + ai * 128 + m * 16) * PITCH + C_MERGED + col0;
; #pragma unroll
;                     for (int bj = 0; bj < 2; ++bj) {
;                         const u32x4 g = gq[m][bj];
;                         const f32x4 a0 = acc[ai][bj][m][0], a1 = acc[ai][bj][m][1];
;                         float r0 = bflo(g.x) * a0[0], r1 = bfhi(g.x) * a0[1], r2 = bflo(g.y) * a0[2], r3 = bfhi(g.y) * a0[3];
;                         float r4 = bflo(g.z) * a1[0], r5 = bfhi(g.z) * a1[1], r6 = bflo(g.w) * a1[2], r7 = bfhi(g.w) * a1[3];
;                         if (z > 1) { const u32x4 pm_ = mq[m][bj];
;                             r0 += bflo(pm_.x); r1 += bfhi(pm_.x); r2 += bflo(pm_.y); r3 += bfhi(pm_.y); r4 += bflo(pm_.z); r5 += bfhi(pm_.z); r6 += bflo(pm_.w); r7 += bfhi(pm_.w); }
;                         u32x4 w; w.x = cvtpk(r0, r1); w.y = cvtpk(r2, r3); w.z = cvtpk(r4, r5); w.w = cvtpk(r6, r7);
;                         *(u32x4*)(mp + bj * 128) = w;
;                     } }
.Lmo_h2e_5:
	v_cvt_pk_bf16_f32 v218, v218, v219
	v_cvt_pk_bf16_f32 v219, v220, v221
	v_cvt_pk_bf16_f32 v220, v222, v223
	v_cvt_pk_bf16_f32 v221, v224, v225
	global_store_dwordx4 v[252:253], v[218:221], off offset:1280
	v_lshl_add_u64 v[252:253], v[252:253], 0, s[98:99]
	s_and_b64 vcc, exec, s[44:45]
	s_cbranch_vccnz .Lmo_h2nm_6
	s_waitcnt vmcnt(9)
	v_lshlrev_b32_e32 v218, 16, v166
	v_and_b32_e32 v219, 0xffff0000, v166
	v_lshlrev_b32_e32 v220, 16, v167
	v_and_b32_e32 v221, 0xffff0000, v167
	v_lshlrev_b32_e32 v222, 16, v168
	v_and_b32_e32 v223, 0xffff0000, v168
	v_lshlrev_b32_e32 v224, 16, v169
	v_and_b32_e32 v225, 0xffff0000, v169
	v_pk_mul_f32 v[218:219], v[14:15], v[218:219]
	v_pk_mul_f32 v[220:221], v[16:17], v[220:221]
	v_pk_mul_f32 v[222:223], v[10:11], v[222:223]
	v_pk_mul_f32 v[224:225], v[12:13], v[224:225]
	v_lshlrev_b32_e32 v166, 16, v134
	v_and_b32_e32 v167, 0xffff0000, v134
	v_pk_add_f32 v[218:219], v[218:219], v[166:167]
	v_lshlrev_b32_e32 v168, 16, v135
	v_and_b32_e32 v169, 0xffff0000, v135
	v_pk_add_f32 v[220:221], v[220:221], v[168:169]
	v_lshlrev_b32_e32 v166, 16, v136
	v_and_b32_e32 v167, 0xffff0000, v136
	v_pk_add_f32 v[222:223], v[222:223], v[166:167]
	v_lshlrev_b32_e32 v168, 16, v137
	v_and_b32_e32 v169, 0xffff0000, v137
	v_pk_add_f32 v[224:225], v[224:225], v[168:169]
	s_branch .Lmo_h2e_6
.Lmo_h2nm_6:
	s_waitcnt vmcnt(8)
	v_lshlrev_b32_e32 v218, 16, v166
	v_and_b32_e32 v219, 0xffff0000, v166
	v_lshlrev_b32_e32 v220, 16, v167
	v_and_b32_e32 v221, 0xffff0000, v167
	v_lshlrev_b32_e32 v222, 16, v168
	v_and_b32_e32 v223, 0xffff0000, v168
	v_lshlrev_b32_e32 v224, 16, v169
	v_and_b32_e32 v225, 0xffff0000, v169
	v_pk_mul_f32 v[218:219], v[14:15], v[218:219]
	v_pk_mul_f32 v[220:221], v[16:17], v[220:221]
	v_pk_mul_f32 v[222:223], v[10:11], v[222:223]
	v_pk_mul_f32 v[224:225], v[12:13], v[224:225]
.Lmo_h2e_6:
	v_cvt_pk_bf16_f32 v218, v218, v219
	v_cvt_pk_bf16_f32 v219, v220, v221
	v_cvt_pk_bf16_f32 v220, v222, v223
	v_cvt_pk_bf16_f32 v221, v224, v225
	global_store_dwordx4 v[252:253], v[218:221], off offset:1024
	s_nop 1
	s_and_b64 vcc, exec, s[44:45]
	s_cbranch_vccnz .Lmo_h2nm_7
	s_waitcnt vmcnt(7)
	v_lshlrev_b32_e32 v218, 16, v162
	v_and_b32_e32 v219, 0xffff0000, v162
	v_lshlrev_b32_e32 v220, 16, v163
	v_and_b32_e32 v221, 0xffff0000, v163
	v_lshlrev_b32_e32 v222, 16, v164
	v_and_b32_e32 v223, 0xffff0000, v164
	v_lshlrev_b32_e32 v224, 16, v165
	v_and_b32_e32 v225, 0xffff0000, v165
	v_pk_mul_f32 v[218:219], v[6:7], v[218:219]
	v_pk_mul_f32 v[220:221], v[8:9], v[220:221]
	v_pk_mul_f32 v[222:223], v[2:3], v[222:223]
	v_pk_mul_f32 v[224:225], v[4:5], v[224:225]
	v_lshlrev_b32_e32 v162, 16, v130
	v_and_b32_e32 v163, 0xffff0000, v130
	v_pk_add_f32 v[218:219], v[218:219], v[162:163]
	v_lshlrev_b32_e32 v164, 16, v131
	v_and_b32_e32 v165, 0xffff0000, v131
	v_pk_add_f32 v[220:221], v[220:221], v[164:165]
	v_lshlrev_b32_e32 v162, 16, v132
	v_and_b32_e32 v163, 0xffff0000, v132
	v_pk_add_f32 v[222:223], v[222:223], v[162:163]
	v_lshlrev_b32_e32 v164, 16, v133
	v_and_b32_e32 v165, 0xffff0000, v133
	v_pk_add_f32 v[224:225], v[224:225], v[164:165]
	s_branch .Lmo_h2e_7
.Lmo_h2nm_7:
	s_waitcnt vmcnt(7)
	v_lshlrev_b32_e32 v218, 16, v162
	v_and_b32_e32 v219, 0xffff0000, v162
	v_lshlrev_b32_e32 v220, 16, v163
	v_and_b32_e32 v221, 0xffff0000, v163
	v_lshlrev_b32_e32 v222, 16, v164
	v_and_b32_e32 v223, 0xffff0000, v164
	v_lshlrev_b32_e32 v224, 16, v165
	v_and_b32_e32 v225, 0xffff0000, v165
	v_pk_mul_f32 v[218:219], v[6:7], v[218:219]
	v_pk_mul_f32 v[220:221], v[8:9], v[220:221]
	v_pk_mul_f32 v[222:223], v[2:3], v[222:223]
	v_pk_mul_f32 v[224:225], v[4:5], v[224:225]
.Lmo_h2e_7:
	s_mov_b64 s[22:23], 0x400
	v_lshl_add_u64 v[134:135], v[252:253], 0, s[22:23]
	v_cvt_pk_bf16_f32 v130, v218, v219
	v_cvt_pk_bf16_f32 v131, v220, v221
	v_cvt_pk_bf16_f32 v132, v222, v223
	v_mov_b32_e32 v136, v224
	v_mov_b32_e32 v137, v225
	s_mov_b64 s[22:23], 0
